# attention-prep row loop: row prefetch distance 1 -> 3 (loop unrolled by 3 with rotating row buffers)
# speedup vs baseline: 1.0068x; 1.0011x over previous
; #define PIN(i) ((const float*)(const GASP float*)karg_q(i))
; __device__ __forceinline__ int obid() { int b = blockIdx.x; asm volatile("" : "+s"(b)); return b; }
; __device__ __forceinline__ void p3_prep(const Params& P, int l) {
;     ...
;     const int sub = lane & 7;
;     float gA[8], gB[8], gC[8];
;     { const float* nqg = PIN(9) + l * 64 + sub * 8; const float* nkg = PIN(10) + l * 64 + sub * 8;
; #pragma unroll
;       for (int j = 0; j < 8; ++j) { gA[j] = lane < 48 ? nqg[j] * NA_QSCALE : nkg[j]; gB[j] = nkg[j]; }
;       const float* gc = lane < 32 ? PIN(12) + l * 256 + lane * 8 : (lane < 48 ? PIN(14) + l * 128 + (lane - 32) * 8 : PIN(17) + l * 96 + 64 + ((lane - 48) & 3) * 8);
; #pragma unroll
;       for (int j = 0; j < 8; ++j) gC[j] = gc[j]; }
;     for (int row = obid() * 8 + wave; row < MTOK; row += gridDim.x * 8) {
;         bf16_t* u = U + (size_t)row * NINP;
;         const bool latent = row < NLAT;
;         const uint4 ra = *(const uint4*)(u + lane * 8);
;         const uint4 rb = *(const uint4*)(u + 512 + (lane & 31) * 8);
;         const uint4 rc = *(const uint4*)(u + OCQ + (lane < 52 ? lane : 51) * 8);
.LBB0_575:
	s_or_b64 exec, exec, s[2:3]
	global_load_dwordx4 v[2:5], v[6:7], off offset:16
	s_nop 0
	global_load_dwordx4 v[6:9], v[6:7], off
	v_ashrrev_i32_e32 v1, 6, v10
	s_mov_b32 s2, s63
	s_nop 0
	v_lshl_add_u32 v1, s2, 3, v1
	v_cmp_gt_i32_e32 vcc, s10, v1
	s_and_saveexec_b64 s[2:3], vcc
	s_cbranch_execz .LBB0_592
	v_min_u32_e32 v13, 51, v11
	v_and_b32_e32 v10, 1, v10
	v_readlane_b32 s6, v255, 9
	v_lshlrev_b32_e32 v34, 3, v11
	v_and_b32_e32 v12, 0xf8, v12
	v_cmp_gt_u32_e64 s[46:47], 52, v11
	v_lshlrev_b32_e32 v38, 3, v13
	v_cmp_gt_u32_e64 s[48:49], 50, v11
	v_cmp_eq_u32_e64 s[50:51], 0, v10
	v_lshlrev_b32_e32 v10, 4, v11
	v_mov_b32_e32 v11, v0
	v_readlane_b32 s7, v255, 10
	v_lshl_add_u64 v[30:31], s[56:57], 0, v[10:11]
	s_mov_b64 s[16:17], 0
	v_lshl_add_u64 v[32:33], s[6:7], 0, v[10:11]
	v_lshlrev_b32_e32 v34, 1, v34
	v_lshlrev_b32_e32 v36, 1, v12
	v_lshlrev_b32_e32 v38, 1, v38
	v_mul_lo_u32 v92, v1, s90
	v_add_u32_e32 v93, v92, v34
	global_load_dwordx4 v[80:83], v93, s[68:69]
	v_add_u32_e32 v93, v92, v36
	global_load_dwordx4 v[84:87], v93, s[68:69] offset:1024
	v_add_u32_e32 v93, v92, v38
	global_load_dwordx4 v[88:91], v93, s[68:69] offset:2304
	v_add_u32_e32 v92, 0x900000, v92
	v_add_u32_e32 v93, v92, v34
	global_load_dwordx4 v[116:119], v93, s[68:69]
	v_add_u32_e32 v93, v92, v36
	global_load_dwordx4 v[120:123], v93, s[68:69] offset:1024
	v_add_u32_e32 v93, v92, v38
	global_load_dwordx4 v[124:127], v93, s[68:69] offset:2304
	v_add_u32_e32 v92, 0x900000, v92
	v_add_u32_e32 v93, v92, v34
	global_load_dwordx4 v[128:131], v93, s[68:69]
	v_add_u32_e32 v93, v92, v36
	global_load_dwordx4 v[132:135], v93, s[68:69] offset:1024
	v_add_u32_e32 v93, v92, v38
	global_load_dwordx4 v[136:139], v93, s[68:69] offset:2304
	s_waitcnt vmcnt(0)
	s_branch .Lprep_entry

; template <int K> __device__ __forceinline__ float swz(float v) { return __int_as_float(__builtin_amdgcn_ds_swizzle(__float_as_int(v), (K << 10) | 0x1f)); }
; __device__ __forceinline__ int obid() { int b = blockIdx.x; asm volatile("" : "+s"(b)); return b; }
; __device__ __forceinline__ void unpack8(const uint4 r, float (&v)[8]) { v[0] = bflo(r.x); v[1] = bfhi(r.x); v[2] = bflo(r.y); v[3] = bfhi(r.y); v[4] = bflo(r.z); v[5] = bfhi(r.z); v[6] = bflo(r.w); v[7] = bfhi(r.w); }
; __device__ __forceinline__ uint4 pack8(const float (&v)[8]) { uint4 w; w.x = pk2(v[0], v[1]); w.y = pk2(v[2], v[3]); w.z = pk2(v[4], v[5]); w.w = pk2(v[6], v[7]); return w; }
; __device__ __forceinline__ void p3_prep(const Params& P, int l) {
;     ...
;     for (int row = obid() * 8 + wave; row < MTOK; row += gridDim.x * 8) {
;         bf16_t* u = U + (size_t)row * NINP;
;         const bool latent = row < NLAT;
;         const uint4 ra = *(const uint4*)(u + lane * 8);
;         const uint4 rb = *(const uint4*)(u + 512 + (lane & 31) * 8);
;         const uint4 rc = *(const uint4*)(u + OCQ + (lane < 52 ? lane : 51) * 8);
;         float v[8];
;         unpack8(ra, v);
;         { float s = 0.f;
; #pragma unroll
;           for (int j = 0; j < 8; ++j) s += v[j] * v[j];
;           s += swz<1>(s); s += swz<2>(s); s += swz<4>(s);
;           const float rs = rsqrtf(s * (1.0f / 64.0f) + EPS);
; #pragma unroll
;           for (int j = 0; j < 8; ++j) v[j] = v[j] * rs * gA[j];
;           *(uint4*)(u + lane * 8) = pack8(v); }
;         unpack8(rb, v);
;         { float s = 0.f;
; #pragma unroll
;           for (int j = 0; j < 8; ++j) s += v[j] * v[j];
;           s += swz<1>(s); s += swz<2>(s); s += swz<4>(s);
;           const float rs = rsqrtf(s * (1.0f / 64.0f) + EPS);
; #pragma unroll
;           for (int j = 0; j < 8; ++j) v[j] = v[j] * rs * gB[j];
;           if (lane < 32) *(uint4*)(u + 512 + lane * 8) = pack8(v); }
.LBB0_578:
	s_waitcnt vmcnt(41)
.Lprep_entry:
	v_mov_b64_e32 v[10:11], s[68:69]
	v_mad_i64_i32 v[10:11], s[6:7], v1, s90, v[10:11]
	s_waitcnt lgkmcnt(8)
	v_mov_b32_e32 v35, v0
	v_lshl_add_u64 v[40:41], v[10:11], 0, v[34:35]
	s_waitcnt lgkmcnt(0)
	v_mov_b32_e32 v37, v0
	v_lshl_add_u64 v[12:13], v[10:11], 0, v[36:37]
	v_mov_b32_e32 v39, v0
	v_lshl_add_u64 v[10:11], v[10:11], 0, v[38:39]
	s_mov_b64 s[98:99], 0x1b00000
	v_lshl_add_u64 v[92:93], v[40:41], 0, s[98:99]
	v_lshl_add_u64 v[94:95], v[12:13], 0, s[98:99]
	v_lshl_add_u64 v[96:97], v[10:11], 0, s[98:99]
	v_bfe_u32 v98, v1, 6, 5
	v_and_b32_e32 v99, 63, v1
	v_cndmask_b32_e64 v98, v99, v98, s[48:49]
	v_lshlrev_b32_e32 v98, 6, v98
	global_load_dwordx4 v[100:103], v98, s[22:23] offset:48
	global_load_dwordx4 v[104:107], v98, s[22:23] offset:32
	global_load_dwordx4 v[108:111], v98, s[22:23] offset:16
	global_load_dwordx4 v[112:115], v98, s[22:23]
	v_mov_b32_e32 v42, v80
	v_mov_b32_e32 v43, v81
	v_mov_b32_e32 v44, v82
	v_mov_b32_e32 v45, v83
	v_mov_b32_e32 v50, v84
	v_mov_b32_e32 v51, v85
	v_mov_b32_e32 v52, v86
	v_mov_b32_e32 v53, v87
	v_mov_b32_e32 v10, v88
	v_mov_b32_e32 v11, v89
	v_mov_b32_e32 v12, v90
	v_mov_b32_e32 v13, v91
	global_load_dwordx4 v[80:83], v[92:93], off
	global_load_dwordx4 v[84:87], v[94:95], off offset:1024
	global_load_dwordx4 v[88:91], v[96:97], off offset:2304
	v_lshlrev_b32_e32 v46, 16, v42
	v_and_b32_e32 v47, 0xffff0000, v42
	v_lshlrev_b32_e32 v42, 16, v43
	v_and_b32_e32 v43, 0xffff0000, v43
	v_pk_mul_f32 v[60:61], v[46:47], v[46:47]
	v_pk_mul_f32 v[58:59], v[42:43], v[42:43]
	v_add_f32_e32 v35, v60, v61
	v_lshlrev_b32_e32 v48, 16, v44
	v_and_b32_e32 v49, 0xffff0000, v44
	v_add_f32_e32 v35, v35, v58
	v_pk_mul_f32 v[56:57], v[48:49], v[48:49]
	v_add_f32_e32 v35, v59, v35
	v_lshlrev_b32_e32 v44, 16, v45
	v_and_b32_e32 v45, 0xffff0000, v45
	v_add_f32_e32 v35, v56, v35
	v_pk_mul_f32 v[54:55], v[44:45], v[44:45]
	v_add_f32_e32 v35, v57, v35
	v_add_f32_e32 v35, v54, v35
	v_add_f32_e32 v35, v55, v35
	ds_swizzle_b32 v37, v35 offset:swizzle(SWAP,1)
	s_waitcnt lgkmcnt(0)
	v_add_f32_e32 v35, v35, v37
	ds_swizzle_b32 v37, v35 offset:swizzle(SWAP,2)
	s_waitcnt lgkmcnt(0)
	v_add_f32_e32 v35, v35, v37
	ds_swizzle_b32 v37, v35 offset:swizzle(SWAP,4)
	s_waitcnt lgkmcnt(0)
	v_add_f32_e32 v35, v35, v37
	v_mov_b32_e32 v37, 0x358637bd
	v_fmamk_f32 v35, v35, 0x3c800000, v37
	v_cmp_gt_f32_e32 vcc, s88, v35
	v_mul_f32_e32 v37, 0x4b800000, v35
	s_nop 0
	v_cndmask_b32_e32 v35, v35, v37, vcc
	v_rsq_f32_e32 v35, v35
	s_nop 0
	v_mul_f32_e32 v37, 0x45800000, v35
	v_cndmask_b32_e32 v54, v35, v37, vcc
	v_pk_mul_f32 v[42:43], v[54:55], v[42:43] op_sel_hi:[0,1]
	v_pk_mul_f32 v[56:57], v[20:21], v[42:43]
	v_pk_mul_f32 v[42:43], v[54:55], v[48:49] op_sel_hi:[0,1]
	v_pk_mul_f32 v[46:47], v[54:55], v[46:47] op_sel_hi:[0,1]
	v_pk_mul_f32 v[48:49], v[24:25], v[42:43]
	v_pk_mul_f32 v[42:43], v[54:55], v[44:45] op_sel_hi:[0,1]
	v_pk_mul_f32 v[46:47], v[16:17], v[46:47]
	v_pk_mul_f32 v[54:55], v[28:29], v[42:43]
	v_cvt_pk_bf16_f32 v44, v48, v49
	s_nop 0
	v_lshlrev_b32_e32 v48, 16, v50
	v_and_b32_e32 v49, 0xffff0000, v50
	v_cvt_pk_bf16_f32 v42, v46, v47
	v_cvt_pk_bf16_f32 v43, v56, v57
	v_cvt_pk_bf16_f32 v45, v54, v55
	v_lshlrev_b32_e32 v46, 16, v51
	v_and_b32_e32 v47, 0xffff0000, v51
	v_pk_mul_f32 v[50:51], v[48:49], v[48:49]
	global_store_dwordx4 v[40:41], v[42:45], off
	v_add_f32_e32 v35, v50, v51
	s_nop 0
	v_lshlrev_b32_e32 v44, 16, v52
	v_and_b32_e32 v45, 0xffff0000, v52
	v_lshlrev_b32_e32 v42, 16, v53
	v_and_b32_e32 v43, 0xffff0000, v53
	v_pk_mul_f32 v[52:53], v[46:47], v[46:47]
	v_pk_mul_f32 v[54:55], v[44:45], v[44:45]
	v_add_f32_e32 v35, v35, v52
	v_add_f32_e32 v35, v53, v35
	v_add_f32_e32 v35, v54, v35
	v_pk_mul_f32 v[56:57], v[42:43], v[42:43]
	v_add_f32_e32 v35, v55, v35
	v_add_f32_e32 v35, v56, v35
	v_add_f32_e32 v35, v57, v35
	ds_swizzle_b32 v37, v35 offset:swizzle(SWAP,1)
	s_waitcnt lgkmcnt(0)
	v_add_f32_e32 v35, v35, v37
	ds_swizzle_b32 v37, v35 offset:swizzle(SWAP,2)
	s_waitcnt lgkmcnt(0)
	v_add_f32_e32 v35, v35, v37
	ds_swizzle_b32 v37, v35 offset:swizzle(SWAP,4)
	s_and_saveexec_b64 s[20:21], s[42:43]
	s_cbranch_execz .LBB0_580
	s_waitcnt lgkmcnt(0)
	v_add_f32_e32 v35, v35, v37
	v_mov_b32_e32 v37, 0x358637bd
	v_fmamk_f32 v35, v35, 0x3c800000, v37
	v_mul_f32_e32 v37, 0x4b800000, v35
	v_cmp_gt_f32_e32 vcc, s88, v35
	s_nop 1
	v_cndmask_b32_e32 v35, v35, v37, vcc
	v_rsq_f32_e32 v35, v35
	s_nop 0
	v_mul_f32_e32 v37, 0x45800000, v35
	v_cndmask_b32_e32 v50, v35, v37, vcc
	v_pk_mul_f32 v[48:49], v[50:51], v[48:49] op_sel_hi:[0,1]
	v_pk_mul_f32 v[46:47], v[50:51], v[46:47] op_sel_hi:[0,1]
	v_pk_mul_f32 v[44:45], v[50:51], v[44:45] op_sel_hi:[0,1]
	v_pk_mul_f32 v[42:43], v[50:51], v[42:43] op_sel_hi:[0,1]
	v_pk_mul_f32 v[48:49], v[14:15], v[48:49]
	v_pk_mul_f32 v[46:47], v[18:19], v[46:47]
	v_pk_mul_f32 v[44:45], v[22:23], v[44:45]
	v_pk_mul_f32 v[50:51], v[26:27], v[42:43]
	v_cvt_pk_bf16_f32 v42, v48, v49
	v_cvt_pk_bf16_f32 v43, v46, v47
	v_cvt_pk_bf16_f32 v44, v44, v45
	v_cvt_pk_bf16_f32 v45, v50, v51
	global_store_dwordx4 v[40:41], v[42:45], off offset:1024

; template <int K> __device__ __forceinline__ float swz(float v) { return __int_as_float(__builtin_amdgcn_ds_swizzle(__float_as_int(v), (K << 10) | 0x1f)); }
; __device__ __forceinline__ int obid() { int b = blockIdx.x; asm volatile("" : "+s"(b)); return b; }
; __device__ __forceinline__ uint4 pack8(const float (&v)[8]) { uint4 w; w.x = pk2(v[0], v[1]); w.y = pk2(v[2], v[3]); w.z = pk2(v[4], v[5]); w.w = pk2(v[6], v[7]); return w; }
; __device__ __forceinline__ void p3_prep(const Params& P, int l) {
;     ...
;     for (int row = obid() * 8 + wave; row < MTOK; row += gridDim.x * 8) {
;     ...
;           for (int j = 0; j < 8; ++j) v[j] = v[j] * rs * gC[j];
;           float pv[8];
; #pragma unroll
;           for (int j = 0; j < 8; ++j) pv[j] = swz<1>(v[j]);
;           if (lane < 48) { *(uint4*)(A2 + (size_t)row * 384 + lane * 8) = pack8(v); }
.LBB0_590:
	s_andn2_saveexec_b64 s[20:21], s[20:21]
	s_cbranch_execz .Lp3u1_LBB0_577
	v_cvt_pk_bf16_f32 v10, v10, v11
	v_cvt_pk_bf16_f32 v11, v12, v13
	v_cvt_pk_bf16_f32 v12, v40, v41
	v_cvt_pk_bf16_f32 v13, v42, v43
	v_mad_i64_i32 v[40:41], s[6:7], v1, s87, v[32:33]
	global_store_dwordx4 v[40:41], v[10:13], off
	s_branch .Lp3u1_LBB0_577
.Lp3u1_LBB0_577:
	s_or_b64 exec, exec, s[20:21]
	v_add_u32_e32 v1, s72, v1
	v_cmp_lt_i32_e32 vcc, s11, v1
	s_or_b64 s[16:17], vcc, s[16:17]
	s_andn2_b64 exec, exec, s[16:17]
	s_cbranch_execz .LBB0_592

; template <int K> __device__ __forceinline__ float swz(float v) { return __int_as_float(__builtin_amdgcn_ds_swizzle(__float_as_int(v), (K << 10) | 0x1f)); }
; __device__ __forceinline__ int obid() { int b = blockIdx.x; asm volatile("" : "+s"(b)); return b; }
; __device__ __forceinline__ void unpack8(const uint4 r, float (&v)[8]) { v[0] = bflo(r.x); v[1] = bfhi(r.x); v[2] = bflo(r.y); v[3] = bfhi(r.y); v[4] = bflo(r.z); v[5] = bfhi(r.z); v[6] = bflo(r.w); v[7] = bfhi(r.w); }
; __device__ __forceinline__ uint4 pack8(const float (&v)[8]) { uint4 w; w.x = pk2(v[0], v[1]); w.y = pk2(v[2], v[3]); w.z = pk2(v[4], v[5]); w.w = pk2(v[6], v[7]); return w; }
; __device__ __forceinline__ void p3_prep(const Params& P, int l) {
;     ...
;     for (int row = obid() * 8 + wave; row < MTOK; row += gridDim.x * 8) {
;         bf16_t* u = U + (size_t)row * NINP;
;         const bool latent = row < NLAT;
;         const uint4 ra = *(const uint4*)(u + lane * 8);
;         const uint4 rb = *(const uint4*)(u + 512 + (lane & 31) * 8);
;         const uint4 rc = *(const uint4*)(u + OCQ + (lane < 52 ? lane : 51) * 8);
;         float v[8];
;         unpack8(ra, v);
;         { float s = 0.f;
; #pragma unroll
;           for (int j = 0; j < 8; ++j) s += v[j] * v[j];
;           s += swz<1>(s); s += swz<2>(s); s += swz<4>(s);
;           const float rs = rsqrtf(s * (1.0f / 64.0f) + EPS);
; #pragma unroll
;           for (int j = 0; j < 8; ++j) v[j] = v[j] * rs * gA[j];
;           *(uint4*)(u + lane * 8) = pack8(v); }
;         unpack8(rb, v);
;         { float s = 0.f;
; #pragma unroll
;           for (int j = 0; j < 8; ++j) s += v[j] * v[j];
;           s += swz<1>(s); s += swz<2>(s); s += swz<4>(s);
;           const float rs = rsqrtf(s * (1.0f / 64.0f) + EPS);
; #pragma unroll
;           for (int j = 0; j < 8; ++j) v[j] = v[j] * rs * gB[j];
;           if (lane < 32) *(uint4*)(u + 512 + lane * 8) = pack8(v); }
.Lp3u1_Lprep_entry:
	v_mov_b64_e32 v[10:11], s[68:69]
	v_mad_i64_i32 v[10:11], s[6:7], v1, s90, v[10:11]
	s_waitcnt lgkmcnt(8)
	v_mov_b32_e32 v35, v0
	v_lshl_add_u64 v[40:41], v[10:11], 0, v[34:35]
	s_waitcnt lgkmcnt(0)
	v_mov_b32_e32 v37, v0
	v_lshl_add_u64 v[12:13], v[10:11], 0, v[36:37]
	v_mov_b32_e32 v39, v0
	v_lshl_add_u64 v[10:11], v[10:11], 0, v[38:39]
	s_mov_b64 s[98:99], 0x1b00000
	v_lshl_add_u64 v[92:93], v[40:41], 0, s[98:99]
	v_lshl_add_u64 v[94:95], v[12:13], 0, s[98:99]
	v_lshl_add_u64 v[96:97], v[10:11], 0, s[98:99]
	v_bfe_u32 v98, v1, 6, 5
	v_and_b32_e32 v99, 63, v1
	v_cndmask_b32_e64 v98, v99, v98, s[48:49]
	v_lshlrev_b32_e32 v98, 6, v98
	global_load_dwordx4 v[100:103], v98, s[22:23] offset:48
	global_load_dwordx4 v[104:107], v98, s[22:23] offset:32
	global_load_dwordx4 v[108:111], v98, s[22:23] offset:16
	global_load_dwordx4 v[112:115], v98, s[22:23]
	v_mov_b32_e32 v42, v116
	v_mov_b32_e32 v43, v117
	v_mov_b32_e32 v44, v118
	v_mov_b32_e32 v45, v119
	v_mov_b32_e32 v50, v120
	v_mov_b32_e32 v51, v121
	v_mov_b32_e32 v52, v122
	v_mov_b32_e32 v53, v123
	v_mov_b32_e32 v10, v124
	v_mov_b32_e32 v11, v125
	v_mov_b32_e32 v12, v126
	v_mov_b32_e32 v13, v127
	global_load_dwordx4 v[116:119], v[92:93], off
	global_load_dwordx4 v[120:123], v[94:95], off offset:1024
	global_load_dwordx4 v[124:127], v[96:97], off offset:2304
	v_lshlrev_b32_e32 v46, 16, v42
	v_and_b32_e32 v47, 0xffff0000, v42
	v_lshlrev_b32_e32 v42, 16, v43
	v_and_b32_e32 v43, 0xffff0000, v43
	v_pk_mul_f32 v[60:61], v[46:47], v[46:47]
	v_pk_mul_f32 v[58:59], v[42:43], v[42:43]
	v_add_f32_e32 v35, v60, v61
	v_lshlrev_b32_e32 v48, 16, v44
	v_and_b32_e32 v49, 0xffff0000, v44
	v_add_f32_e32 v35, v35, v58
	v_pk_mul_f32 v[56:57], v[48:49], v[48:49]
	v_add_f32_e32 v35, v59, v35
	v_lshlrev_b32_e32 v44, 16, v45
	v_and_b32_e32 v45, 0xffff0000, v45
	v_add_f32_e32 v35, v56, v35
	v_pk_mul_f32 v[54:55], v[44:45], v[44:45]
	v_add_f32_e32 v35, v57, v35
	v_add_f32_e32 v35, v54, v35
	v_add_f32_e32 v35, v55, v35
	ds_swizzle_b32 v37, v35 offset:swizzle(SWAP,1)
	s_waitcnt lgkmcnt(0)
	v_add_f32_e32 v35, v35, v37
	ds_swizzle_b32 v37, v35 offset:swizzle(SWAP,2)
	s_waitcnt lgkmcnt(0)
	v_add_f32_e32 v35, v35, v37
	ds_swizzle_b32 v37, v35 offset:swizzle(SWAP,4)
	s_waitcnt lgkmcnt(0)
	v_add_f32_e32 v35, v35, v37
	v_mov_b32_e32 v37, 0x358637bd
	v_fmamk_f32 v35, v35, 0x3c800000, v37
	v_cmp_gt_f32_e32 vcc, s88, v35
	v_mul_f32_e32 v37, 0x4b800000, v35
	s_nop 0
	v_cndmask_b32_e32 v35, v35, v37, vcc
	v_rsq_f32_e32 v35, v35
	s_nop 0
	v_mul_f32_e32 v37, 0x45800000, v35
	v_cndmask_b32_e32 v54, v35, v37, vcc
	v_pk_mul_f32 v[42:43], v[54:55], v[42:43] op_sel_hi:[0,1]
	v_pk_mul_f32 v[56:57], v[20:21], v[42:43]
	v_pk_mul_f32 v[42:43], v[54:55], v[48:49] op_sel_hi:[0,1]
	v_pk_mul_f32 v[46:47], v[54:55], v[46:47] op_sel_hi:[0,1]
	v_pk_mul_f32 v[48:49], v[24:25], v[42:43]
	v_pk_mul_f32 v[42:43], v[54:55], v[44:45] op_sel_hi:[0,1]
	v_pk_mul_f32 v[46:47], v[16:17], v[46:47]
	v_pk_mul_f32 v[54:55], v[28:29], v[42:43]
	v_cvt_pk_bf16_f32 v44, v48, v49
	s_nop 0
	v_lshlrev_b32_e32 v48, 16, v50
	v_and_b32_e32 v49, 0xffff0000, v50
	v_cvt_pk_bf16_f32 v42, v46, v47
	v_cvt_pk_bf16_f32 v43, v56, v57
	v_cvt_pk_bf16_f32 v45, v54, v55
	v_lshlrev_b32_e32 v46, 16, v51
	v_and_b32_e32 v47, 0xffff0000, v51
	v_pk_mul_f32 v[50:51], v[48:49], v[48:49]
	global_store_dwordx4 v[40:41], v[42:45], off
	v_add_f32_e32 v35, v50, v51
	s_nop 0
	v_lshlrev_b32_e32 v44, 16, v52
	v_and_b32_e32 v45, 0xffff0000, v52
	v_lshlrev_b32_e32 v42, 16, v53
	v_and_b32_e32 v43, 0xffff0000, v53
	v_pk_mul_f32 v[52:53], v[46:47], v[46:47]
	v_pk_mul_f32 v[54:55], v[44:45], v[44:45]
	v_add_f32_e32 v35, v35, v52
	v_add_f32_e32 v35, v53, v35
	v_add_f32_e32 v35, v54, v35
	v_pk_mul_f32 v[56:57], v[42:43], v[42:43]
	v_add_f32_e32 v35, v55, v35
	v_add_f32_e32 v35, v56, v35
	v_add_f32_e32 v35, v57, v35
	ds_swizzle_b32 v37, v35 offset:swizzle(SWAP,1)
	s_waitcnt lgkmcnt(0)
	v_add_f32_e32 v35, v35, v37
	ds_swizzle_b32 v37, v35 offset:swizzle(SWAP,2)
	s_waitcnt lgkmcnt(0)
	v_add_f32_e32 v35, v35, v37
	ds_swizzle_b32 v37, v35 offset:swizzle(SWAP,4)
	s_and_saveexec_b64 s[20:21], s[42:43]
	s_cbranch_execz .Lp3u1_LBB0_580
	s_waitcnt lgkmcnt(0)
	v_add_f32_e32 v35, v35, v37
	v_mov_b32_e32 v37, 0x358637bd
	v_fmamk_f32 v35, v35, 0x3c800000, v37
	v_mul_f32_e32 v37, 0x4b800000, v35
	v_cmp_gt_f32_e32 vcc, s88, v35
	s_nop 1
	v_cndmask_b32_e32 v35, v35, v37, vcc
	v_rsq_f32_e32 v35, v35
	s_nop 0
	v_mul_f32_e32 v37, 0x45800000, v35
	v_cndmask_b32_e32 v50, v35, v37, vcc
	v_pk_mul_f32 v[48:49], v[50:51], v[48:49] op_sel_hi:[0,1]
	v_pk_mul_f32 v[46:47], v[50:51], v[46:47] op_sel_hi:[0,1]
	v_pk_mul_f32 v[44:45], v[50:51], v[44:45] op_sel_hi:[0,1]
	v_pk_mul_f32 v[42:43], v[50:51], v[42:43] op_sel_hi:[0,1]
	v_pk_mul_f32 v[48:49], v[14:15], v[48:49]
	v_pk_mul_f32 v[46:47], v[18:19], v[46:47]
	v_pk_mul_f32 v[44:45], v[22:23], v[44:45]
	v_pk_mul_f32 v[50:51], v[26:27], v[42:43]
	v_cvt_pk_bf16_f32 v42, v48, v49
	v_cvt_pk_bf16_f32 v43, v46, v47
	v_cvt_pk_bf16_f32 v44, v44, v45
	v_cvt_pk_bf16_f32 v45, v50, v51
	global_store_dwordx4 v[40:41], v[42:45], off offset:1024

; template <int K> __device__ __forceinline__ float swz(float v) { return __int_as_float(__builtin_amdgcn_ds_swizzle(__float_as_int(v), (K << 10) | 0x1f)); }
; __device__ __forceinline__ int obid() { int b = blockIdx.x; asm volatile("" : "+s"(b)); return b; }
; __device__ __forceinline__ uint4 pack8(const float (&v)[8]) { uint4 w; w.x = pk2(v[0], v[1]); w.y = pk2(v[2], v[3]); w.z = pk2(v[4], v[5]); w.w = pk2(v[6], v[7]); return w; }
; __device__ __forceinline__ void p3_prep(const Params& P, int l) {
;     ...
;     for (int row = obid() * 8 + wave; row < MTOK; row += gridDim.x * 8) {
;     ...
;           for (int j = 0; j < 8; ++j) v[j] = v[j] * rs * gC[j];
;           float pv[8];
; #pragma unroll
;           for (int j = 0; j < 8; ++j) pv[j] = swz<1>(v[j]);
;           if (lane < 48) { *(uint4*)(A2 + (size_t)row * 384 + lane * 8) = pack8(v); }
.Lp3u1_LBB0_590:
	s_andn2_saveexec_b64 s[20:21], s[20:21]
	s_cbranch_execz .Lp3u2_LBB0_577
	v_cvt_pk_bf16_f32 v10, v10, v11
	v_cvt_pk_bf16_f32 v11, v12, v13
	v_cvt_pk_bf16_f32 v12, v40, v41
	v_cvt_pk_bf16_f32 v13, v42, v43
	v_mad_i64_i32 v[40:41], s[6:7], v1, s87, v[32:33]
	global_store_dwordx4 v[40:41], v[10:13], off
	s_branch .Lp3u2_LBB0_577
.Lp3u2_LBB0_577:
	s_or_b64 exec, exec, s[20:21]
	v_add_u32_e32 v1, s72, v1
	v_cmp_lt_i32_e32 vcc, s11, v1
	s_or_b64 s[16:17], vcc, s[16:17]
	s_andn2_b64 exec, exec, s[16:17]
	s_cbranch_execz .LBB0_592

; template <int K> __device__ __forceinline__ float swz(float v) { return __int_as_float(__builtin_amdgcn_ds_swizzle(__float_as_int(v), (K << 10) | 0x1f)); }
; __device__ __forceinline__ int obid() { int b = blockIdx.x; asm volatile("" : "+s"(b)); return b; }
; __device__ __forceinline__ void unpack8(const uint4 r, float (&v)[8]) { v[0] = bflo(r.x); v[1] = bfhi(r.x); v[2] = bflo(r.y); v[3] = bfhi(r.y); v[4] = bflo(r.z); v[5] = bfhi(r.z); v[6] = bflo(r.w); v[7] = bfhi(r.w); }
; __device__ __forceinline__ uint4 pack8(const float (&v)[8]) { uint4 w; w.x = pk2(v[0], v[1]); w.y = pk2(v[2], v[3]); w.z = pk2(v[4], v[5]); w.w = pk2(v[6], v[7]); return w; }
; __device__ __forceinline__ void p3_prep(const Params& P, int l) {
;     ...
;     for (int row = obid() * 8 + wave; row < MTOK; row += gridDim.x * 8) {
;         bf16_t* u = U + (size_t)row * NINP;
;         const bool latent = row < NLAT;
;         const uint4 ra = *(const uint4*)(u + lane * 8);
;         const uint4 rb = *(const uint4*)(u + 512 + (lane & 31) * 8);
;         const uint4 rc = *(const uint4*)(u + OCQ + (lane < 52 ? lane : 51) * 8);
;         float v[8];
;         unpack8(ra, v);
;         { float s = 0.f;
; #pragma unroll
;           for (int j = 0; j < 8; ++j) s += v[j] * v[j];
;           s += swz<1>(s); s += swz<2>(s); s += swz<4>(s);
;           const float rs = rsqrtf(s * (1.0f / 64.0f) + EPS);
; #pragma unroll
;           for (int j = 0; j < 8; ++j) v[j] = v[j] * rs * gA[j];
;           *(uint4*)(u + lane * 8) = pack8(v); }
;         unpack8(rb, v);
;         { float s = 0.f;
; #pragma unroll
;           for (int j = 0; j < 8; ++j) s += v[j] * v[j];
;           s += swz<1>(s); s += swz<2>(s); s += swz<4>(s);
;           const float rs = rsqrtf(s * (1.0f / 64.0f) + EPS);
; #pragma unroll
;           for (int j = 0; j < 8; ++j) v[j] = v[j] * rs * gB[j];
;           if (lane < 32) *(uint4*)(u + 512 + lane * 8) = pack8(v); }
.Lp3u2_Lprep_entry:
	v_mov_b64_e32 v[10:11], s[68:69]
	v_mad_i64_i32 v[10:11], s[6:7], v1, s90, v[10:11]
	s_waitcnt lgkmcnt(8)
	v_mov_b32_e32 v35, v0
	v_lshl_add_u64 v[40:41], v[10:11], 0, v[34:35]
	s_waitcnt lgkmcnt(0)
	v_mov_b32_e32 v37, v0
	v_lshl_add_u64 v[12:13], v[10:11], 0, v[36:37]
	v_mov_b32_e32 v39, v0
	v_lshl_add_u64 v[10:11], v[10:11], 0, v[38:39]
	s_mov_b64 s[98:99], 0x1b00000
	v_lshl_add_u64 v[92:93], v[40:41], 0, s[98:99]
	v_lshl_add_u64 v[94:95], v[12:13], 0, s[98:99]
	v_lshl_add_u64 v[96:97], v[10:11], 0, s[98:99]
	v_bfe_u32 v98, v1, 6, 5
	v_and_b32_e32 v99, 63, v1
	v_cndmask_b32_e64 v98, v99, v98, s[48:49]
	v_lshlrev_b32_e32 v98, 6, v98
	global_load_dwordx4 v[100:103], v98, s[22:23] offset:48
	global_load_dwordx4 v[104:107], v98, s[22:23] offset:32
	global_load_dwordx4 v[108:111], v98, s[22:23] offset:16
	global_load_dwordx4 v[112:115], v98, s[22:23]
	v_mov_b32_e32 v42, v128
	v_mov_b32_e32 v43, v129
	v_mov_b32_e32 v44, v130
	v_mov_b32_e32 v45, v131
	v_mov_b32_e32 v50, v132
	v_mov_b32_e32 v51, v133
	v_mov_b32_e32 v52, v134
	v_mov_b32_e32 v53, v135
	v_mov_b32_e32 v10, v136
	v_mov_b32_e32 v11, v137
	v_mov_b32_e32 v12, v138
	v_mov_b32_e32 v13, v139
	global_load_dwordx4 v[128:131], v[92:93], off
	global_load_dwordx4 v[132:135], v[94:95], off offset:1024
	global_load_dwordx4 v[136:139], v[96:97], off offset:2304
	v_lshlrev_b32_e32 v46, 16, v42
	v_and_b32_e32 v47, 0xffff0000, v42
	v_lshlrev_b32_e32 v42, 16, v43
	v_and_b32_e32 v43, 0xffff0000, v43
	v_pk_mul_f32 v[60:61], v[46:47], v[46:47]
	v_pk_mul_f32 v[58:59], v[42:43], v[42:43]
	v_add_f32_e32 v35, v60, v61
	v_lshlrev_b32_e32 v48, 16, v44
	v_and_b32_e32 v49, 0xffff0000, v44
	v_add_f32_e32 v35, v35, v58
	v_pk_mul_f32 v[56:57], v[48:49], v[48:49]
	v_add_f32_e32 v35, v59, v35
	v_lshlrev_b32_e32 v44, 16, v45
	v_and_b32_e32 v45, 0xffff0000, v45
	v_add_f32_e32 v35, v56, v35
	v_pk_mul_f32 v[54:55], v[44:45], v[44:45]
	v_add_f32_e32 v35, v57, v35
	v_add_f32_e32 v35, v54, v35
	v_add_f32_e32 v35, v55, v35
	ds_swizzle_b32 v37, v35 offset:swizzle(SWAP,1)
	s_waitcnt lgkmcnt(0)
	v_add_f32_e32 v35, v35, v37
	ds_swizzle_b32 v37, v35 offset:swizzle(SWAP,2)
	s_waitcnt lgkmcnt(0)
	v_add_f32_e32 v35, v35, v37
	ds_swizzle_b32 v37, v35 offset:swizzle(SWAP,4)
	s_waitcnt lgkmcnt(0)
	v_add_f32_e32 v35, v35, v37
	v_mov_b32_e32 v37, 0x358637bd
	v_fmamk_f32 v35, v35, 0x3c800000, v37
	v_cmp_gt_f32_e32 vcc, s88, v35
	v_mul_f32_e32 v37, 0x4b800000, v35
	s_nop 0
	v_cndmask_b32_e32 v35, v35, v37, vcc
	v_rsq_f32_e32 v35, v35
	s_nop 0
	v_mul_f32_e32 v37, 0x45800000, v35
	v_cndmask_b32_e32 v54, v35, v37, vcc
	v_pk_mul_f32 v[42:43], v[54:55], v[42:43] op_sel_hi:[0,1]
	v_pk_mul_f32 v[56:57], v[20:21], v[42:43]
	v_pk_mul_f32 v[42:43], v[54:55], v[48:49] op_sel_hi:[0,1]
	v_pk_mul_f32 v[46:47], v[54:55], v[46:47] op_sel_hi:[0,1]
	v_pk_mul_f32 v[48:49], v[24:25], v[42:43]
	v_pk_mul_f32 v[42:43], v[54:55], v[44:45] op_sel_hi:[0,1]
	v_pk_mul_f32 v[46:47], v[16:17], v[46:47]
	v_pk_mul_f32 v[54:55], v[28:29], v[42:43]
	v_cvt_pk_bf16_f32 v44, v48, v49
	s_nop 0
	v_lshlrev_b32_e32 v48, 16, v50
	v_and_b32_e32 v49, 0xffff0000, v50
	v_cvt_pk_bf16_f32 v42, v46, v47
	v_cvt_pk_bf16_f32 v43, v56, v57
	v_cvt_pk_bf16_f32 v45, v54, v55
	v_lshlrev_b32_e32 v46, 16, v51
	v_and_b32_e32 v47, 0xffff0000, v51
	v_pk_mul_f32 v[50:51], v[48:49], v[48:49]
	global_store_dwordx4 v[40:41], v[42:45], off
	v_add_f32_e32 v35, v50, v51
	s_nop 0
	v_lshlrev_b32_e32 v44, 16, v52
	v_and_b32_e32 v45, 0xffff0000, v52
	v_lshlrev_b32_e32 v42, 16, v53
	v_and_b32_e32 v43, 0xffff0000, v53
	v_pk_mul_f32 v[52:53], v[46:47], v[46:47]
	v_pk_mul_f32 v[54:55], v[44:45], v[44:45]
	v_add_f32_e32 v35, v35, v52
	v_add_f32_e32 v35, v53, v35
	v_add_f32_e32 v35, v54, v35
	v_pk_mul_f32 v[56:57], v[42:43], v[42:43]
	v_add_f32_e32 v35, v55, v35
	v_add_f32_e32 v35, v56, v35
	v_add_f32_e32 v35, v57, v35
	ds_swizzle_b32 v37, v35 offset:swizzle(SWAP,1)
	s_waitcnt lgkmcnt(0)
	v_add_f32_e32 v35, v35, v37
	ds_swizzle_b32 v37, v35 offset:swizzle(SWAP,2)
	s_waitcnt lgkmcnt(0)
	v_add_f32_e32 v35, v35, v37
	ds_swizzle_b32 v37, v35 offset:swizzle(SWAP,4)
	s_and_saveexec_b64 s[20:21], s[42:43]
	s_cbranch_execz .Lp3u2_LBB0_580
	s_waitcnt lgkmcnt(0)
	v_add_f32_e32 v35, v35, v37
	v_mov_b32_e32 v37, 0x358637bd
	v_fmamk_f32 v35, v35, 0x3c800000, v37
	v_mul_f32_e32 v37, 0x4b800000, v35
	v_cmp_gt_f32_e32 vcc, s88, v35
	s_nop 1
	v_cndmask_b32_e32 v35, v35, v37, vcc
	v_rsq_f32_e32 v35, v35
	s_nop 0
	v_mul_f32_e32 v37, 0x45800000, v35
	v_cndmask_b32_e32 v50, v35, v37, vcc
	v_pk_mul_f32 v[48:49], v[50:51], v[48:49] op_sel_hi:[0,1]
	v_pk_mul_f32 v[46:47], v[50:51], v[46:47] op_sel_hi:[0,1]
	v_pk_mul_f32 v[44:45], v[50:51], v[44:45] op_sel_hi:[0,1]
	v_pk_mul_f32 v[42:43], v[50:51], v[42:43] op_sel_hi:[0,1]
	v_pk_mul_f32 v[48:49], v[14:15], v[48:49]
	v_pk_mul_f32 v[46:47], v[18:19], v[46:47]
	v_pk_mul_f32 v[44:45], v[22:23], v[44:45]
	v_pk_mul_f32 v[50:51], v[26:27], v[42:43]
	v_cvt_pk_bf16_f32 v42, v48, v49
	v_cvt_pk_bf16_f32 v43, v46, v47
	v_cvt_pk_bf16_f32 v44, v44, v45
	v_cvt_pk_bf16_f32 v45, v50, v51
	global_store_dwordx4 v[40:41], v[42:45], off offset:1024
